# odd in-XCD workgroups start the residual-update GEMM phases (down, final down, out) one s_sleep 127 later so the epilogue bursts of the two halves alternate
# speedup vs baseline: 1.0022x; 1.0022x over previous
.LBB0_284:
	s_andn2_b64 vcc, exec, s[4:5]
	s_cbranch_vccnz .LBB0_324
	s_lshl_b32 s2, s27, 10
	v_lshl_add_u32 v1, v12, 4, s2
	v_ashrrev_i32_e32 v0, 31, v1
	v_lshrrev_b32_e32 v0, 22, v0
	v_add_u32_e32 v0, v1, v0
	v_ashrrev_i32_e32 v13, 10, v0
	v_mul_i32_i24_e32 v0, 0x400, v13
	v_sub_u32_e32 v0, v1, v0
	v_lshrrev_b32_e32 v2, 4, v0
	v_bitop3_b32 v0, v2, v0, 32 bitop3:0x6c
	v_ashrrev_i32_e32 v4, 31, v0
	v_lshrrev_b32_e32 v4, 26, v4
	v_add_u32_e32 v4, v0, v4
	v_lshlrev_b32_e32 v2, 3, v13
	v_ashrrev_i32_e32 v15, 6, v4
	v_and_b32_e32 v4, 0xc0, v4
	v_and_b32_e32 v2, -16, v2
	v_sub_u32_e32 v0, v0, v4
	v_mov_b32_e32 v7, 1
	v_add_u32_e32 v2, v15, v2
	v_lshlrev_b32_e32 v5, 5, v13
	v_ashrrev_i16_sdwa v0, v7, sext(v0) dst_sel:DWORD dst_unused:UNUSED_PAD src0_sel:DWORD src1_sel:BYTE_0
	v_and_b32_e32 v14, 32, v5
	v_bfe_i32 v16, v0, 0, 16
	v_lshlrev_b32_e32 v0, 1, v2
	v_lshrrev_b32_e32 v5, 2, v2
	v_and_b32_e32 v6, 3, v15
	s_mov_b32 s4, 0x7fffe0
	v_and_b32_e32 v0, 24, v0
	v_and_b32_e32 v5, 4, v5
	v_and_or_b32 v6, v2, s4, v6
	v_or3_b32 v5, v6, v5, v0
	s_movk_i32 s5, 0x1600
	v_add_u32_e32 v4, v14, v16
	v_mul_lo_u32 v0, v2, s5
	v_mul_u32_u24_e32 v2, 0x1600, v5
	v_add_u32_e32 v1, 0x2000, v1
	v_add_lshl_u32 v0, v4, v0, 1
	v_add_lshl_u32 v2, v2, v4, 1
	v_ashrrev_i32_e32 v4, 31, v1
	v_lshrrev_b32_e32 v4, 22, v4
	v_add_u32_e32 v4, v1, v4
	v_ashrrev_i32_e32 v17, 10, v4
	v_mul_i32_i24_e32 v4, 0x400, v17
	v_sub_u32_e32 v1, v1, v4
	v_lshrrev_b32_e32 v4, 4, v1
	v_bitop3_b32 v1, v4, v1, 32 bitop3:0x6c
	v_ashrrev_i32_e32 v5, 31, v1
	v_lshrrev_b32_e32 v5, 26, v5
	v_add_u32_e32 v5, v1, v5
	v_ashrrev_i32_e32 v19, 6, v5
	v_and_b32_e32 v5, 0xffc0, v5
	v_sub_u32_e32 v1, v1, v5
	v_lshrrev_b16_e32 v5, 7, v1
	v_lshlrev_b32_e32 v4, 3, v17
	v_and_b32_e32 v5, 1, v5
	v_and_b32_e32 v4, -16, v4
	v_add_u16_e32 v1, v1, v5
	v_add_u32_e32 v4, v19, v4
	v_lshlrev_b32_e32 v6, 5, v17
	v_ashrrev_i16_sdwa v1, v7, sext(v1) dst_sel:DWORD dst_unused:UNUSED_PAD src0_sel:DWORD src1_sel:BYTE_0
	v_and_b32_e32 v7, 3, v19
	s_ashr_i32 s10, s27, 2
	v_and_b32_e32 v18, 32, v6
	v_lshlrev_b32_e32 v5, 1, v4
	v_lshrrev_b32_e32 v6, 2, v4
	v_and_or_b32 v7, v4, s4, v7
	v_mul_lo_u32 v4, v4, s5
	s_mul_i32 s5, s47, 0x2c0000
	s_mul_hi_i32 s4, s47, 0x2c0000
	s_add_u32 s18, s25, s5
	v_bfe_i32 v20, v1, 0, 16
	v_and_b32_e32 v5, 24, v5
	v_and_b32_e32 v6, 4, v6
	s_addc_u32 s19, s26, s4
	s_add_i32 s28, s2, 0
	v_add_u32_e32 v1, v18, v20
	v_or3_b32 v5, v7, v6, v5
	s_add_i32 m0, s28, 0x10000
	s_waitcnt vmcnt(0)
	v_add_lshl_u32 v188, v1, v4, 1
	v_mul_u32_u24_e32 v4, 0x1600, v5
	v_readlane_b32 s98, v253, 2
	s_nop 3
	s_bitcmp1_b32 s98, 3
	s_cbranch_scc0 .Lstg_skip_2
	s_sleep 127
.Lstg_skip_2:
	global_load_lds_dwordx4 v2, s[18:19]
	s_add_i32 m0, s28, 0x12000
	v_add_lshl_u32 v190, v4, v1, 1
	s_add_u32 s4, s18, 0x160000
	global_load_lds_dwordx4 v190, s[18:19]
	s_addc_u32 s5, s19, 0
	s_add_i32 m0, s28, 0x14000
	s_mul_i32 s7, s46, 0x2c0000
	global_load_lds_dwordx4 v2, s[4:5]
	s_add_i32 m0, s28, 0x16000
	s_mul_hi_i32 s6, s46, 0x2c0000
	s_add_u32 s16, s1, s7
	s_addc_u32 s17, s24, s6
	s_add_i32 s29, s28, 0x2000
	global_load_lds_dwordx4 v190, s[4:5]
	s_mov_b32 m0, s28
	s_add_u32 s4, s16, 0x160000
	global_load_lds_dwordx4 v0, s[16:17]
	s_mov_b32 m0, s29
	s_addc_u32 s5, s17, 0
	s_add_i32 s30, s28, 0x4000
	global_load_lds_dwordx4 v188, s[16:17]
	s_mov_b32 m0, s30
	s_add_i32 s31, s28, 0x6000
	global_load_lds_dwordx4 v0, s[4:5]
	s_mov_b32 m0, s31
	v_mov_b32_e32 v191, v3
	global_load_lds_dwordx4 v188, s[4:5]
	v_mov_b32_e32 v1, v3
	v_mov_b32_e32 v189, v3
	s_cmp_eq_u32 s10, 1
	v_mov_b32_e32 v252, 1
	v_lshl_add_u64 v[10:11], s[18:19], 0, v[2:3]
	v_lshl_add_u64 v[8:9], s[18:19], 0, v[190:191]
	v_lshl_add_u64 v[4:5], s[16:17], 0, v[0:1]
	s_cselect_b64 s[4:5], -1, 0
	s_cmp_lg_u32 s10, 1
	v_lshl_add_u64 v[6:7], s[16:17], 0, v[188:189]
	s_cbranch_scc1 .LBB0_287
	s_barrier

.LBB0_331:
	s_lshl_b32 s22, s27, 10
	v_lshl_add_u32 v1, v20, 4, s22
	v_ashrrev_i32_e32 v0, 31, v1
	v_lshrrev_b32_e32 v0, 22, v0
	v_add_u32_e32 v0, v1, v0
	v_ashrrev_i32_e32 v12, 10, v0
	v_mul_i32_i24_e32 v0, 0x400, v12
	v_sub_u32_e32 v0, v1, v0
	v_lshrrev_b32_e32 v2, 4, v0
	v_bitop3_b32 v0, v2, v0, 32 bitop3:0x6c
	v_ashrrev_i32_e32 v4, 31, v0
	v_lshrrev_b32_e32 v4, 26, v4
	v_add_u32_e32 v4, v0, v4
	v_lshlrev_b32_e32 v2, 3, v12
	v_ashrrev_i32_e32 v14, 6, v4
	v_and_b32_e32 v4, 0xc0, v4
	v_and_b32_e32 v2, -16, v2
	v_sub_u32_e32 v0, v0, v4
	v_mov_b32_e32 v7, 1
	v_add_u32_e32 v2, v14, v2
	v_lshlrev_b32_e32 v5, 5, v12
	v_ashrrev_i16_sdwa v0, v7, sext(v0) dst_sel:DWORD dst_unused:UNUSED_PAD src0_sel:DWORD src1_sel:BYTE_0
	v_and_b32_e32 v13, 32, v5
	v_bfe_i32 v15, v0, 0, 16
	v_lshlrev_b32_e32 v0, 1, v2
	v_lshrrev_b32_e32 v5, 2, v2
	v_and_b32_e32 v6, 3, v14
	s_mov_b32 s5, 0x7fffe0
	v_and_b32_e32 v0, 24, v0
	v_and_b32_e32 v5, 4, v5
	v_and_or_b32 v6, v2, s5, v6
	v_or3_b32 v5, v6, v5, v0
	s_movk_i32 s10, 0x1600
	v_add_u32_e32 v4, v13, v15
	v_mul_lo_u32 v0, v2, s10
	v_mul_u32_u24_e32 v2, 0x1600, v5
	v_add_u32_e32 v1, 0x2000, v1
	v_add_lshl_u32 v0, v4, v0, 1
	v_add_lshl_u32 v2, v2, v4, 1
	v_ashrrev_i32_e32 v4, 31, v1
	v_lshrrev_b32_e32 v4, 22, v4
	v_add_u32_e32 v4, v1, v4
	v_ashrrev_i32_e32 v16, 10, v4
	v_mul_i32_i24_e32 v4, 0x400, v16
	v_sub_u32_e32 v1, v1, v4
	v_lshrrev_b32_e32 v4, 4, v1
	v_bitop3_b32 v1, v4, v1, 32 bitop3:0x6c
	v_ashrrev_i32_e32 v5, 31, v1
	v_lshrrev_b32_e32 v5, 26, v5
	v_add_u32_e32 v5, v1, v5
	v_ashrrev_i32_e32 v18, 6, v5
	v_and_b32_e32 v5, 0xffc0, v5
	v_sub_u32_e32 v1, v1, v5
	v_lshrrev_b16_e32 v5, 7, v1
	v_lshlrev_b32_e32 v4, 3, v16
	v_and_b32_e32 v5, 1, v5
	s_ashr_i32 s4, s6, 3
	v_and_b32_e32 v4, -16, v4
	v_add_u16_e32 v1, v1, v5
	v_add_u32_e32 v4, v18, v4
	v_ashrrev_i16_sdwa v1, v7, sext(v1) dst_sel:DWORD dst_unused:UNUSED_PAD src0_sel:DWORD src1_sel:BYTE_0
	v_and_b32_e32 v7, 3, v18
	s_add_i32 s4, s7, s4
	v_and_or_b32 v7, v4, s5, v7
	s_ashr_i32 s5, s4, 31
	s_lshr_b32 s5, s5, 27
	s_add_i32 s5, s4, s5
	s_ashr_i32 s7, s5, 5
	s_andn2_b32 s5, s5, 31
	s_sub_i32 s4, s4, s5
	s_bfe_i32 s5, s4, 0x80000
	s_bfe_u32 s5, s5, 0x2000d
	v_lshlrev_b32_e32 v6, 5, v16
	s_add_i32 s5, s4, s5
	v_and_b32_e32 v17, 32, v6
	v_lshlrev_b32_e32 v5, 1, v4
	v_lshrrev_b32_e32 v6, 2, v4
	v_mul_lo_u32 v4, v4, s10
	s_lshl_b32 s10, s7, 2
	s_bfe_i32 s7, s5, 0x80000
	s_and_b32 s5, s5, 0xfc
	s_sub_i32 s4, s4, s5
	s_sext_i32_i16 s11, s7
	s_sext_i32_i8 s4, s4
	s_add_i32 s41, s10, s4
	s_ashr_i32 s4, s11, 2
	s_ashr_i32 s6, s27, 2
	s_lshr_b32 s7, s11, 2
	s_mul_hi_i32 s5, s4, 0x2c0000
	s_mul_i32 s4, s4, 0x2c0000
	s_add_u32 s16, s25, s4
	v_bfe_i32 v19, v1, 0, 16
	v_and_b32_e32 v5, 24, v5
	v_and_b32_e32 v6, 4, v6
	s_addc_u32 s17, s26, s5
	s_add_i32 s23, s22, 0
	v_add_u32_e32 v1, v17, v19
	v_or3_b32 v5, v7, v6, v5
	s_add_i32 m0, s23, 0x10000
	s_waitcnt vmcnt(0)
	v_add_lshl_u32 v196, v1, v4, 1
	v_mul_u32_u24_e32 v4, 0x1600, v5
	v_readlane_b32 s98, v253, 2
	s_nop 3
	s_bitcmp1_b32 s98, 3
	s_cbranch_scc0 .Lstg_skip_1
	s_sleep 127
.Lstg_skip_1:
	global_load_lds_dwordx4 v2, s[16:17]
	s_add_i32 m0, s23, 0x12000
	v_add_lshl_u32 v198, v4, v1, 1
	s_add_u32 s4, s16, 0x160000
	global_load_lds_dwordx4 v198, s[16:17]
	s_addc_u32 s5, s17, 0
	s_add_i32 m0, s23, 0x14000
	s_mul_i32 s12, s41, 0x2c0000
	global_load_lds_dwordx4 v2, s[4:5]
	s_add_i32 m0, s23, 0x16000
	s_mul_hi_i32 s10, s41, 0x2c0000
	s_add_u32 s14, s1, s12
	s_addc_u32 s15, s24, s10
	s_add_i32 s28, s23, 0x2000
	global_load_lds_dwordx4 v198, s[4:5]
	s_mov_b32 m0, s23
	s_add_u32 s4, s14, 0x160000
	global_load_lds_dwordx4 v0, s[14:15]
	s_mov_b32 m0, s28
	s_addc_u32 s5, s15, 0
	s_add_i32 s29, s23, 0x4000
	global_load_lds_dwordx4 v196, s[14:15]
	s_mov_b32 m0, s29
	s_add_i32 s30, s23, 0x6000
	global_load_lds_dwordx4 v0, s[4:5]
	s_mov_b32 m0, s30
	v_mov_b32_e32 v199, v3
	global_load_lds_dwordx4 v196, s[4:5]
	v_mov_b32_e32 v1, v3
	v_mov_b32_e32 v197, v3
	s_cmp_eq_u32 s6, 1
	v_mov_b32_e32 v252, 1
	v_lshl_add_u64 v[10:11], s[16:17], 0, v[2:3]
	v_lshl_add_u64 v[8:9], s[16:17], 0, v[198:199]
	v_lshl_add_u64 v[4:5], s[14:15], 0, v[0:1]
	s_cselect_b64 s[4:5], -1, 0
	s_cmp_lg_u32 s6, 1
	v_lshl_add_u64 v[6:7], s[14:15], 0, v[196:197]
	s_cbranch_scc1 .LBB0_333
	s_barrier

.LBB0_997:
	s_andn2_b64 vcc, exec, s[6:7]
	s_cbranch_vccnz .LBB0_1033
	s_add_u32 s1, s11, 0x2d800000
	s_addc_u32 s2, s12, 0
	v_readlane_b32 s6, v255, 3
	s_add_u32 s6, s11, s6
	s_addc_u32 s7, s12, 0
	s_add_u32 s28, s6, 0x29a00000
	s_addc_u32 s29, s7, 0
	s_lshl_b32 s30, s10, 10
	v_lshl_add_u32 v1, v4, 4, s30
	v_ashrrev_i32_e32 v0, 31, v1
	v_lshrrev_b32_e32 v0, 22, v0
	v_add_u32_e32 v0, v1, v0
	v_ashrrev_i32_e32 v5, 10, v0
	v_mul_i32_i24_e32 v0, 0x400, v5
	v_sub_u32_e32 v0, v1, v0
	v_lshrrev_b32_e32 v2, 4, v0
	v_bitop3_b32 v0, v2, v0, 32 bitop3:0x6c
	v_ashrrev_i32_e32 v6, 31, v0
	v_lshrrev_b32_e32 v6, 26, v6
	v_add_u32_e32 v7, v0, v6
	v_lshlrev_b32_e32 v2, 3, v5
	v_ashrrev_i32_e32 v6, 6, v7
	v_and_b32_e32 v7, 0xc0, v7
	v_and_b32_e32 v2, -16, v2
	v_sub_u32_e32 v0, v0, v7
	v_mov_b32_e32 v14, 1
	v_add_u32_e32 v2, v6, v2
	v_ashrrev_i16_sdwa v0, v14, sext(v0) dst_sel:DWORD dst_unused:UNUSED_PAD src0_sel:DWORD src1_sel:BYTE_0
	v_lshlrev_b32_e32 v8, 5, v5
	v_bfe_i32 v7, v0, 0, 16
	v_lshlrev_b32_e32 v0, 1, v2
	v_lshrrev_b32_e32 v9, 2, v2
	v_and_b32_e32 v10, 3, v6
	s_mov_b32 s6, 0xfffe0
	v_and_b32_e32 v8, 32, v8
	v_and_b32_e32 v0, 24, v0
	v_and_b32_e32 v9, 4, v9
	v_and_or_b32 v10, v2, s6, v10
	v_or3_b32 v9, v10, v9, v0
	v_add_lshl_u32 v8, v8, v7, 1
	v_add_u32_e32 v1, 0x2000, v1
	v_lshl_add_u32 v0, v2, 12, v8
	v_lshl_add_u32 v2, v9, 12, v8
	v_ashrrev_i32_e32 v8, 31, v1
	v_lshrrev_b32_e32 v8, 22, v8
	v_add_u32_e32 v8, v1, v8
	v_ashrrev_i32_e32 v8, 10, v8
	v_mul_i32_i24_e32 v9, 0x400, v8
	v_sub_u32_e32 v1, v1, v9
	v_lshrrev_b32_e32 v9, 4, v1
	v_bitop3_b32 v1, v9, v1, 32 bitop3:0x6c
	v_lshlrev_b32_e32 v9, 3, v8
	v_and_b32_e32 v10, -16, v9
	v_ashrrev_i32_e32 v9, 31, v1
	v_lshrrev_b32_e32 v9, 26, v9
	v_add_u32_e32 v11, v1, v9
	v_ashrrev_i32_e32 v9, 6, v11
	v_add_u32_e32 v12, v9, v10
	v_lshlrev_b32_e32 v10, 5, v8
	v_and_b32_e32 v13, 32, v10
	v_and_b32_e32 v10, 0xffc0, v11
	v_sub_u32_e32 v1, v1, v10
	v_lshrrev_b16_e32 v10, 7, v1
	v_and_b32_e32 v10, 1, v10
	v_add_u16_e32 v1, v1, v10
	v_ashrrev_i16_sdwa v1, v14, sext(v1) dst_sel:DWORD dst_unused:UNUSED_PAD src0_sel:DWORD src1_sel:BYTE_0
	v_and_b32_e32 v14, 3, v9
	s_ashr_i32 s19, s18, 31
	s_ashr_i32 s21, s20, 31
	s_ashr_i32 s8, s10, 2
	v_and_or_b32 v14, v12, s6, v14
	s_lshl_b64 s[6:7], s[18:19], 20
	s_lshl_b64 s[12:13], s[20:21], 20
	s_add_u32 s24, s28, s12
	v_bfe_i32 v10, v1, 0, 16
	v_lshlrev_b32_e32 v1, 1, v12
	v_lshrrev_b32_e32 v11, 2, v12
	s_addc_u32 s25, s29, s13
	s_add_i32 s21, s30, 0
	v_and_b32_e32 v1, 24, v1
	v_and_b32_e32 v11, 4, v11
	s_add_i32 m0, s21, 0x10000
	v_or3_b32 v1, v14, v11, v1
	v_add_lshl_u32 v11, v13, v10, 1
	v_readlane_b32 s98, v253, 2
	s_nop 3
	s_bitcmp1_b32 s98, 3
	s_cbranch_scc0 .Lstg_skip_0
	s_sleep 127
.Lstg_skip_0:
	global_load_lds_dwordx4 v2, s[24:25]
	s_add_i32 m0, s21, 0x12000
	s_waitcnt vmcnt(0)
	v_lshl_add_u32 v190, v1, 12, v11
	s_add_u32 s12, s24, 0x80000
	global_load_lds_dwordx4 v190, s[24:25]
	s_addc_u32 s13, s25, 0
	s_add_i32 m0, s21, 0x14000
	v_lshl_add_u32 v188, v12, 12, v11
	global_load_lds_dwordx4 v2, s[12:13]
	s_add_i32 m0, s21, 0x16000
	s_add_u32 s22, s1, s6
	s_addc_u32 s23, s2, s7
	s_add_i32 s31, s21, 0x2000
	global_load_lds_dwordx4 v190, s[12:13]
	s_mov_b32 m0, s21
	s_add_u32 s6, s22, 0x80000
	global_load_lds_dwordx4 v0, s[22:23]
	s_mov_b32 m0, s31
	s_addc_u32 s7, s23, 0
	s_add_i32 s35, s21, 0x4000
	global_load_lds_dwordx4 v188, s[22:23]
	s_mov_b32 m0, s35
	s_add_i32 s40, s21, 0x6000
	global_load_lds_dwordx4 v0, s[6:7]
	s_mov_b32 m0, s40
	s_cmp_eq_u32 s8, 1
	global_load_lds_dwordx4 v188, s[6:7]
	v_mov_b32_e32 v252, 1
	s_cselect_b64 s[6:7], -1, 0
	s_cmp_lg_u32 s8, 1
	s_cbranch_scc1 .LBB0_1000
	s_barrier
